# v29 + diff-attention epilogue: sub-LN gain loads issued in two batches ahead of the store ladder
# speedup vs baseline: 1.0045x; 1.0045x over previous
.LBB0_1614:
	s_cmpk_gt_u32 s0, 0xff
	s_waitcnt lgkmcnt(0)
	s_barrier
	s_cbranch_scc1 .LBB0_1595
	s_lshl_b32 s0, s0, 8
	v_lshl_add_u32 v5, v207, 2, 0
	s_and_b32 s1, s0, 0xc000
	v_add_u32_e32 v6, s1, v5
	ds_read2st64_b32 v[10:11], v6 offset1:1
	ds_read2st64_b32 v[14:15], v6 offset0:2 offset1:3
	ds_read2st64_b32 v[86:87], v6 offset0:4 offset1:5
	ds_read2st64_b32 v[88:89], v6 offset0:6 offset1:7
	ds_read2st64_b32 v[90:91], v6 offset0:8 offset1:9
	ds_read2st64_b32 v[92:93], v6 offset0:10 offset1:11
	ds_read2st64_b32 v[94:95], v6 offset0:12 offset1:13
	ds_read2st64_b32 v[96:97], v6 offset0:14 offset1:15
	ds_read2st64_b32 v[98:99], v6 offset0:16 offset1:17
	ds_read2st64_b32 v[100:101], v6 offset0:18 offset1:19
	ds_read2st64_b32 v[102:103], v6 offset0:20 offset1:21
	ds_read2st64_b32 v[104:105], v6 offset0:22 offset1:23
	ds_read2st64_b32 v[106:107], v6 offset0:24 offset1:25
	ds_read2st64_b32 v[108:109], v6 offset0:26 offset1:27
	ds_read2st64_b32 v[110:111], v6 offset0:28 offset1:29
	ds_read2st64_b32 v[112:113], v6 offset0:30 offset1:31
	ds_read2st64_b32 v[114:115], v6 offset0:32 offset1:33
	ds_read2st64_b32 v[116:117], v6 offset0:34 offset1:35
	ds_read2st64_b32 v[118:119], v6 offset0:36 offset1:37
	ds_read2st64_b32 v[120:121], v6 offset0:38 offset1:39
	ds_read2st64_b32 v[122:123], v6 offset0:40 offset1:41
	ds_read2st64_b32 v[124:125], v6 offset0:42 offset1:43
	ds_read2st64_b32 v[126:127], v6 offset0:44 offset1:45
	ds_read2st64_b32 v[128:129], v6 offset0:46 offset1:47
	ds_read2st64_b32 v[12:13], v6 offset0:56 offset1:57
	ds_read2st64_b32 v[130:131], v6 offset0:58 offset1:59
	ds_read2st64_b32 v[2:3], v6 offset0:60 offset1:61
	ds_read_b32 v4, v6 offset:15872
	s_waitcnt lgkmcnt(14)
	v_pk_mul_f32 v[10:11], v[160:161], v[10:11]
	s_or_b32 s0, s0, 0x3f00
	v_pk_fma_f32 v[82:83], v[64:65], v[0:1], v[10:11] op_sel_hi:[1,0,1] neg_lo:[0,0,1] neg_hi:[0,0,1]
	v_pk_mul_f32 v[10:11], v[160:161], v[88:89]
	v_add_u32_e32 v5, s0, v5
	v_pk_fma_f32 v[70:71], v[70:71], v[0:1], v[10:11] op_sel_hi:[1,0,1] neg_lo:[0,0,1] neg_hi:[0,0,1]
	v_pk_mul_f32 v[10:11], v[160:161], v[86:87]
	ds_read_b32 v5, v5
	ds_read2st64_b32 v[132:133], v6 offset0:48 offset1:49
	ds_read2st64_b32 v[134:135], v6 offset0:50 offset1:51
	ds_read2st64_b32 v[136:137], v6 offset0:52 offset1:53
	ds_read2st64_b32 v[138:139], v6 offset0:54 offset1:55
	v_pk_fma_f32 v[86:87], v[68:69], v[0:1], v[10:11] op_sel_hi:[1,0,1] neg_lo:[0,0,1] neg_hi:[0,0,1]
	v_pk_mul_f32 v[10:11], v[160:161], v[92:93]
	s_waitcnt lgkmcnt(6)
	v_pk_mul_f32 v[2:3], v[160:161], v[2:3]
	v_pk_fma_f32 v[74:75], v[74:75], v[0:1], v[10:11] op_sel_hi:[1,0,1] neg_lo:[0,0,1] neg_hi:[0,0,1]
	v_pk_mul_f32 v[10:11], v[160:161], v[90:91]
	v_pk_fma_f32 v[6:7], v[28:29], v[0:1], v[2:3] op_sel_hi:[1,0,1] neg_lo:[0,0,1] neg_hi:[0,0,1]
	v_pk_fma_f32 v[90:91], v[72:73], v[0:1], v[10:11] op_sel_hi:[1,0,1] neg_lo:[0,0,1] neg_hi:[0,0,1]
	v_pk_mul_f32 v[10:11], v[160:161], v[96:97]
	s_waitcnt lgkmcnt(4)
	v_pk_mul_f32 v[2:3], v[160:161], v[4:5]
	v_pk_fma_f32 v[68:69], v[78:79], v[0:1], v[10:11] op_sel_hi:[1,0,1] neg_lo:[0,0,1] neg_hi:[0,0,1]
	v_pk_mul_f32 v[10:11], v[160:161], v[94:95]
	v_pk_fma_f32 v[8:9], v[30:31], v[0:1], v[2:3] op_sel_hi:[1,0,1] neg_lo:[0,0,1] neg_hi:[0,0,1]
	v_pk_fma_f32 v[88:89], v[76:77], v[0:1], v[10:11] op_sel_hi:[1,0,1] neg_lo:[0,0,1] neg_hi:[0,0,1]
	v_pk_mul_f32 v[10:11], v[160:161], v[100:101]
	v_pk_mul_f32 v[14:15], v[160:161], v[14:15]
	v_pk_fma_f32 v[64:65], v[50:51], v[0:1], v[10:11] op_sel_hi:[1,0,1] neg_lo:[0,0,1] neg_hi:[0,0,1]
	v_pk_mul_f32 v[10:11], v[160:161], v[98:99]
	v_pk_fma_f32 v[66:67], v[66:67], v[0:1], v[14:15] op_sel_hi:[1,0,1] neg_lo:[0,0,1] neg_hi:[0,0,1]
	v_pk_fma_f32 v[78:79], v[48:49], v[0:1], v[10:11] op_sel_hi:[1,0,1] neg_lo:[0,0,1] neg_hi:[0,0,1]
	v_pk_mul_f32 v[10:11], v[160:161], v[104:105]
	v_pk_mul_f32 v[142:143], v[82:83], v[82:83]
	v_pk_fma_f32 v[54:55], v[54:55], v[0:1], v[10:11] op_sel_hi:[1,0,1] neg_lo:[0,0,1] neg_hi:[0,0,1]
	v_pk_mul_f32 v[10:11], v[160:161], v[102:103]
	v_pk_mul_f32 v[12:13], v[160:161], v[12:13]
	v_pk_fma_f32 v[76:77], v[52:53], v[0:1], v[10:11] op_sel_hi:[1,0,1] neg_lo:[0,0,1] neg_hi:[0,0,1]
	v_pk_mul_f32 v[10:11], v[160:161], v[108:109]
	global_load_dwordx4 v[2:5], v162, s[38:39]
	global_load_dwordx4 v[152:155], v162, s[38:39] offset:32
	global_load_dwordx4 v[156:159], v162, s[38:39] offset:64
	global_load_dwordx4 v[168:171], v162, s[38:39] offset:96
	global_load_dwordx4 v[172:175], v162, s[38:39] offset:128
	global_load_dwordx4 v[176:179], v162, s[38:39] offset:160
	global_load_dwordx4 v[180:183], v162, s[38:39] offset:192
	global_load_dwordx4 v[184:187], v162, s[38:39] offset:224
	global_load_dwordx4 v[188:191], v162, s[38:39] offset:256
	global_load_dwordx4 v[192:195], v162, s[38:39] offset:288
	global_load_dwordx4 v[196:199], v162, s[38:39] offset:320
	v_pk_fma_f32 v[52:53], v[58:59], v[0:1], v[10:11] op_sel_hi:[1,0,1] neg_lo:[0,0,1] neg_hi:[0,0,1]
	v_pk_mul_f32 v[10:11], v[160:161], v[106:107]
	v_pk_mul_f32 v[140:141], v[66:67], v[66:67]
	v_pk_fma_f32 v[72:73], v[56:57], v[0:1], v[10:11] op_sel_hi:[1,0,1] neg_lo:[0,0,1] neg_hi:[0,0,1]
	v_pk_mul_f32 v[10:11], v[160:161], v[112:113]
	v_pk_fma_f32 v[12:13], v[24:25], v[0:1], v[12:13] op_sel_hi:[1,0,1] neg_lo:[0,0,1] neg_hi:[0,0,1]
	v_pk_fma_f32 v[50:51], v[62:63], v[0:1], v[10:11] op_sel_hi:[1,0,1] neg_lo:[0,0,1] neg_hi:[0,0,1]
	v_pk_mul_f32 v[10:11], v[160:161], v[110:111]
	v_pk_mul_f32 v[146:147], v[86:87], v[86:87]
	v_pk_fma_f32 v[60:61], v[60:61], v[0:1], v[10:11] op_sel_hi:[1,0,1] neg_lo:[0,0,1] neg_hi:[0,0,1]
	v_pk_mul_f32 v[10:11], v[160:161], v[116:117]
	v_pk_mul_f32 v[144:145], v[70:71], v[70:71]
	v_pk_fma_f32 v[48:49], v[34:35], v[0:1], v[10:11] op_sel_hi:[1,0,1] neg_lo:[0,0,1] neg_hi:[0,0,1]
	v_pk_mul_f32 v[10:11], v[160:161], v[114:115]
	v_pk_mul_f32 v[148:149], v[90:91], v[90:91]
	v_pk_fma_f32 v[58:59], v[32:33], v[0:1], v[10:11] op_sel_hi:[1,0,1] neg_lo:[0,0,1] neg_hi:[0,0,1]
	v_pk_mul_f32 v[10:11], v[160:161], v[120:121]
	v_pk_mul_f32 v[92:93], v[74:75], v[74:75]
	v_pk_fma_f32 v[32:33], v[38:39], v[0:1], v[10:11] op_sel_hi:[1,0,1] neg_lo:[0,0,1] neg_hi:[0,0,1]
	v_pk_mul_f32 v[10:11], v[160:161], v[118:119]
	v_pk_mul_f32 v[94:95], v[88:89], v[88:89]
	v_pk_fma_f32 v[56:57], v[36:37], v[0:1], v[10:11] op_sel_hi:[1,0,1] neg_lo:[0,0,1] neg_hi:[0,0,1]
	v_pk_mul_f32 v[10:11], v[160:161], v[124:125]
	v_pk_mul_f32 v[96:97], v[68:69], v[68:69]
	v_pk_fma_f32 v[30:31], v[42:43], v[0:1], v[10:11] op_sel_hi:[1,0,1] neg_lo:[0,0,1] neg_hi:[0,0,1]
	v_pk_mul_f32 v[10:11], v[160:161], v[122:123]
	v_pk_mul_f32 v[98:99], v[78:79], v[78:79]
	v_pk_fma_f32 v[38:39], v[40:41], v[0:1], v[10:11] op_sel_hi:[1,0,1] neg_lo:[0,0,1] neg_hi:[0,0,1]
	v_pk_mul_f32 v[10:11], v[160:161], v[128:129]
	v_pk_mul_f32 v[100:101], v[64:65], v[64:65]
	v_pk_fma_f32 v[28:29], v[46:47], v[0:1], v[10:11] op_sel_hi:[1,0,1] neg_lo:[0,0,1] neg_hi:[0,0,1]
	v_pk_mul_f32 v[10:11], v[160:161], v[126:127]
	v_pk_mul_f32 v[102:103], v[76:77], v[76:77]
	v_pk_fma_f32 v[36:37], v[44:45], v[0:1], v[10:11] op_sel_hi:[1,0,1] neg_lo:[0,0,1] neg_hi:[0,0,1]
	s_waitcnt lgkmcnt(2)
	v_pk_mul_f32 v[10:11], v[160:161], v[134:135]
	v_pk_mul_f32 v[104:105], v[54:55], v[54:55]
	v_pk_fma_f32 v[18:19], v[18:19], v[0:1], v[10:11] op_sel_hi:[1,0,1] neg_lo:[0,0,1] neg_hi:[0,0,1]
	v_pk_mul_f32 v[10:11], v[160:161], v[132:133]
	v_pk_mul_f32 v[106:107], v[72:73], v[72:73]
	v_pk_fma_f32 v[34:35], v[16:17], v[0:1], v[10:11] op_sel_hi:[1,0,1] neg_lo:[0,0,1] neg_hi:[0,0,1]
	s_waitcnt lgkmcnt(0)
	v_pk_mul_f32 v[10:11], v[160:161], v[138:139]
	v_pk_mul_f32 v[108:109], v[52:53], v[52:53]
	v_pk_fma_f32 v[14:15], v[22:23], v[0:1], v[10:11] op_sel_hi:[1,0,1] neg_lo:[0,0,1] neg_hi:[0,0,1]
	v_pk_mul_f32 v[10:11], v[160:161], v[136:137]
	v_pk_mul_f32 v[110:111], v[60:61], v[60:61]
	v_pk_fma_f32 v[16:17], v[20:21], v[0:1], v[10:11] op_sel_hi:[1,0,1] neg_lo:[0,0,1] neg_hi:[0,0,1]
	v_pk_mul_f32 v[10:11], v[160:161], v[130:131]
	v_pk_mul_f32 v[62:63], v[50:51], v[50:51]
	v_pk_fma_f32 v[10:11], v[26:27], v[0:1], v[10:11] op_sel_hi:[1,0,1] neg_lo:[0,0,1] neg_hi:[0,0,1]
	v_add_f32_e32 v0, v142, v143
	v_add_f32_e32 v0, v0, v140
	v_add_f32_e32 v0, v0, v141
	v_add_f32_e32 v0, v0, v146
	v_add_f32_e32 v0, v0, v147
	v_add_f32_e32 v0, v0, v144
	v_add_f32_e32 v0, v0, v145
	v_add_f32_e32 v0, v0, v148
	v_add_f32_e32 v0, v0, v149
	v_add_f32_e32 v0, v0, v92
	v_add_f32_e32 v0, v0, v93
	v_add_f32_e32 v0, v0, v94
	v_add_f32_e32 v0, v0, v95
	v_add_f32_e32 v0, v0, v96
	v_add_f32_e32 v0, v0, v97
	v_add_f32_e32 v0, v0, v98
	v_add_f32_e32 v0, v0, v99
	v_add_f32_e32 v0, v0, v100
	v_add_f32_e32 v0, v0, v101
	v_add_f32_e32 v0, v0, v102
	v_add_f32_e32 v0, v0, v103
	v_add_f32_e32 v0, v0, v104
	v_add_f32_e32 v0, v0, v105
	v_add_f32_e32 v0, v0, v106
	v_add_f32_e32 v0, v0, v107
	v_add_f32_e32 v0, v0, v108
	v_add_f32_e32 v0, v0, v109
	v_add_f32_e32 v0, v0, v110
	v_add_f32_e32 v0, v0, v111
	v_add_f32_e32 v0, v0, v62
	v_pk_mul_f32 v[114:115], v[58:59], v[58:59]
	v_add_f32_e32 v0, v0, v63
	v_add_f32_e32 v0, v0, v114
	v_pk_mul_f32 v[112:113], v[48:49], v[48:49]
	v_add_f32_e32 v0, v0, v115
	v_add_f32_e32 v0, v0, v112
	v_pk_mul_f32 v[118:119], v[56:57], v[56:57]
	v_add_f32_e32 v0, v0, v113
	v_add_f32_e32 v0, v0, v118
	v_pk_mul_f32 v[116:117], v[32:33], v[32:33]
	v_add_f32_e32 v0, v0, v119
	v_add_f32_e32 v0, v0, v116
	v_pk_mul_f32 v[40:41], v[38:39], v[38:39]
	v_add_f32_e32 v0, v0, v117
	v_add_f32_e32 v0, v0, v40
	v_pk_mul_f32 v[42:43], v[30:31], v[30:31]
	v_add_f32_e32 v0, v0, v41
	v_add_f32_e32 v0, v0, v42
	v_pk_mul_f32 v[44:45], v[36:37], v[36:37]
	v_add_f32_e32 v0, v0, v43
	v_add_f32_e32 v0, v0, v44
	v_pk_mul_f32 v[46:47], v[28:29], v[28:29]
	v_add_f32_e32 v0, v0, v45
	v_add_f32_e32 v0, v0, v46
	v_pk_mul_f32 v[122:123], v[34:35], v[34:35]
	v_add_f32_e32 v0, v0, v47
	v_add_f32_e32 v0, v0, v122
	v_pk_mul_f32 v[120:121], v[18:19], v[18:19]
	v_add_f32_e32 v0, v0, v123
	v_add_f32_e32 v0, v0, v120
	v_pk_mul_f32 v[20:21], v[16:17], v[16:17]
	v_add_f32_e32 v0, v0, v121
	v_add_f32_e32 v0, v0, v20
	v_pk_mul_f32 v[22:23], v[14:15], v[14:15]
	v_add_f32_e32 v0, v0, v21
	v_add_f32_e32 v0, v0, v22
	v_pk_mul_f32 v[24:25], v[12:13], v[12:13]
	v_add_f32_e32 v0, v0, v23
	v_add_f32_e32 v0, v0, v24
	v_pk_mul_f32 v[26:27], v[10:11], v[10:11]
	v_add_f32_e32 v0, v0, v25
	v_add_f32_e32 v0, v0, v26
	v_pk_mul_f32 v[80:81], v[6:7], v[6:7]
	v_add_f32_e32 v0, v0, v27
	v_add_f32_e32 v0, v0, v80
	v_pk_mul_f32 v[84:85], v[8:9], v[8:9]
	v_add_f32_e32 v0, v0, v81
	v_add_f32_e32 v0, v0, v84
	v_add_f32_e32 v22, v0, v85
	ds_bpermute_b32 v23, v163, v22
	v_lshlrev_b32_e32 v0, 1, v164
	v_lshl_add_u64 v[20:21], s[46:47], 0, v[0:1]
	v_lshl_add_u64 v[20:21], v[20:21], 0, v[166:167]
	s_mov_b64 s[0:1], 0x80
	s_waitcnt lgkmcnt(0)
	v_add_f32_e32 v0, v22, v23
	v_fmamk_f32 v0, v0, 0x3c000000, v205
	v_mul_f32_e32 v22, 0x4b800000, v0
	v_cmp_gt_f32_e32 vcc, s58, v0
	s_nop 1
	v_cndmask_b32_e32 v0, v0, v22, vcc
	v_rsq_f32_e32 v22, v0
	v_lshlrev_b32_e32 v0, 3, v165
	v_lshl_add_u64 v[20:21], v[20:21], 0, v[0:1]
	v_mul_f32_e32 v0, 0x45800000, v22
	v_cndmask_b32_e32 v0, v22, v0, vcc
	v_mul_f32_e32 v0, 0x3f077f5a, v0
	v_pk_mul_f32 v[22:23], v[82:83], v[0:1] op_sel_hi:[1,0]
	v_pk_mul_f32 v[24:25], v[86:87], v[0:1] op_sel_hi:[1,0]
	s_waitcnt vmcnt(0)
	v_pk_mul_f32 v[2:3], v[2:3], v[22:23]
	v_pk_mul_f32 v[22:23], v[66:67], v[0:1] op_sel_hi:[1,0]
	v_cvt_pk_bf16_f32 v2, v2, v3
	v_pk_mul_f32 v[4:5], v[4:5], v[22:23]
	v_lshl_add_u64 v[22:23], v[20:21], 0, 16
	v_cvt_pk_bf16_f32 v3, v4, v5
	global_store_dwordx2 v[20:21], v[2:3], off sc1
	s_nop 1
	v_mov_b64_e32 v[2:3], v[152:153]
	v_mov_b64_e32 v[4:5], v[154:155]
	v_pk_mul_f32 v[26:27], v[74:75], v[0:1] op_sel_hi:[1,0]
	v_pk_mul_f32 v[18:19], v[18:19], v[0:1] op_sel_hi:[1,0]
	v_pk_mul_f32 v[16:17], v[16:17], v[0:1] op_sel_hi:[1,0]
	v_pk_mul_f32 v[14:15], v[14:15], v[0:1] op_sel_hi:[1,0]
	v_pk_mul_f32 v[12:13], v[12:13], v[0:1] op_sel_hi:[1,0]
	v_pk_mul_f32 v[10:11], v[10:11], v[0:1] op_sel_hi:[1,0]
	v_pk_mul_f32 v[6:7], v[6:7], v[0:1] op_sel_hi:[1,0]
	v_pk_mul_f32 v[8:9], v[8:9], v[0:1] op_sel_hi:[1,0]
	v_pk_mul_f32 v[2:3], v[2:3], v[24:25]
	v_pk_mul_f32 v[24:25], v[70:71], v[0:1] op_sel_hi:[1,0]
	v_cvt_pk_bf16_f32 v2, v2, v3
	v_pk_mul_f32 v[4:5], v[4:5], v[24:25]
	v_pk_mul_f32 v[24:25], v[90:91], v[0:1] op_sel_hi:[1,0]
	v_cvt_pk_bf16_f32 v3, v4, v5
	global_store_dwordx2 v[22:23], v[2:3], off sc1
	s_nop 1
	v_mov_b64_e32 v[2:3], v[156:157]
	v_mov_b64_e32 v[4:5], v[158:159]
	v_lshl_add_u64 v[22:23], v[20:21], 0, 32
	v_pk_mul_f32 v[2:3], v[2:3], v[24:25]
	v_pk_mul_f32 v[4:5], v[4:5], v[26:27]
	v_cvt_pk_bf16_f32 v2, v2, v3
	v_cvt_pk_bf16_f32 v3, v4, v5
	global_store_dwordx2 v[22:23], v[2:3], off sc1
	s_nop 1
	v_mov_b64_e32 v[2:3], v[168:169]
	v_mov_b64_e32 v[4:5], v[170:171]
	v_pk_mul_f32 v[24:25], v[88:89], v[0:1] op_sel_hi:[1,0]
	v_pk_mul_f32 v[26:27], v[68:69], v[0:1] op_sel_hi:[1,0]
	v_lshl_add_u64 v[22:23], v[20:21], 0, 48
	v_pk_mul_f32 v[2:3], v[2:3], v[24:25]
	v_pk_mul_f32 v[4:5], v[4:5], v[26:27]
	v_cvt_pk_bf16_f32 v2, v2, v3
	v_cvt_pk_bf16_f32 v3, v4, v5
	global_store_dwordx2 v[22:23], v[2:3], off sc1
	s_nop 1
	v_mov_b64_e32 v[2:3], v[172:173]
	v_mov_b64_e32 v[4:5], v[174:175]
	v_pk_mul_f32 v[24:25], v[78:79], v[0:1] op_sel_hi:[1,0]
	v_pk_mul_f32 v[26:27], v[64:65], v[0:1] op_sel_hi:[1,0]
	v_lshl_add_u64 v[22:23], v[20:21], 0, 64
	v_pk_mul_f32 v[2:3], v[2:3], v[24:25]
	v_pk_mul_f32 v[4:5], v[4:5], v[26:27]
	v_cvt_pk_bf16_f32 v2, v2, v3
	v_cvt_pk_bf16_f32 v3, v4, v5
	global_store_dwordx2 v[22:23], v[2:3], off sc1
	s_nop 1
	v_mov_b64_e32 v[2:3], v[176:177]
	v_mov_b64_e32 v[4:5], v[178:179]
	global_load_dwordx4 v[152:155], v162, s[38:39] offset:352
	global_load_dwordx4 v[156:159], v162, s[38:39] offset:384
	global_load_dwordx4 v[168:171], v162, s[38:39] offset:416
	global_load_dwordx4 v[172:175], v162, s[38:39] offset:448
	global_load_dwordx4 v[176:179], v162, s[38:39] offset:480
	v_pk_mul_f32 v[24:25], v[76:77], v[0:1] op_sel_hi:[1,0]
	v_pk_mul_f32 v[26:27], v[54:55], v[0:1] op_sel_hi:[1,0]
	v_lshl_add_u64 v[22:23], v[20:21], 0, s[42:43]
	v_pk_mul_f32 v[2:3], v[2:3], v[24:25]
	v_pk_mul_f32 v[4:5], v[4:5], v[26:27]
	v_cvt_pk_bf16_f32 v2, v2, v3
	v_cvt_pk_bf16_f32 v3, v4, v5
	global_store_dwordx2 v[22:23], v[2:3], off sc1
	s_nop 1
	v_mov_b64_e32 v[2:3], v[180:181]
	v_mov_b64_e32 v[4:5], v[182:183]
	v_pk_mul_f32 v[24:25], v[72:73], v[0:1] op_sel_hi:[1,0]
	v_pk_mul_f32 v[26:27], v[52:53], v[0:1] op_sel_hi:[1,0]
	v_lshl_add_u64 v[22:23], v[20:21], 0, s[44:45]
	v_pk_mul_f32 v[2:3], v[2:3], v[24:25]
	v_pk_mul_f32 v[4:5], v[4:5], v[26:27]
	v_cvt_pk_bf16_f32 v2, v2, v3
	v_cvt_pk_bf16_f32 v3, v4, v5
	global_store_dwordx2 v[22:23], v[2:3], off sc1
	s_nop 1
	v_mov_b64_e32 v[2:3], v[184:185]
	v_mov_b64_e32 v[4:5], v[186:187]
	v_pk_mul_f32 v[24:25], v[60:61], v[0:1] op_sel_hi:[1,0]
	v_pk_mul_f32 v[26:27], v[50:51], v[0:1] op_sel_hi:[1,0]
	v_lshl_add_u64 v[22:23], v[20:21], 0, s[52:53]
	v_pk_mul_f32 v[2:3], v[24:25], v[2:3]
	v_pk_mul_f32 v[4:5], v[26:27], v[4:5]
	v_cvt_pk_bf16_f32 v2, v2, v3
	v_cvt_pk_bf16_f32 v3, v4, v5
	global_store_dwordx2 v[22:23], v[2:3], off sc1
	s_nop 1
	v_mov_b64_e32 v[2:3], v[188:189]
	v_mov_b64_e32 v[4:5], v[190:191]
	v_pk_mul_f32 v[24:25], v[58:59], v[0:1] op_sel_hi:[1,0]
	v_pk_mul_f32 v[26:27], v[48:49], v[0:1] op_sel_hi:[1,0]
	v_lshl_add_u64 v[22:23], v[20:21], 0, s[0:1]
	s_mov_b64 s[0:1], 0x90
	v_pk_mul_f32 v[2:3], v[24:25], v[2:3]
	v_pk_mul_f32 v[4:5], v[26:27], v[4:5]
	v_cvt_pk_bf16_f32 v2, v2, v3
	v_cvt_pk_bf16_f32 v3, v4, v5
	global_store_dwordx2 v[22:23], v[2:3], off sc1
	s_nop 1
	v_mov_b64_e32 v[2:3], v[192:193]
	v_mov_b64_e32 v[4:5], v[194:195]
	v_pk_mul_f32 v[24:25], v[56:57], v[0:1] op_sel_hi:[1,0]
	v_pk_mul_f32 v[26:27], v[32:33], v[0:1] op_sel_hi:[1,0]
	v_lshl_add_u64 v[22:23], v[20:21], 0, s[0:1]
	s_mov_b64 s[0:1], 0xa0
	v_pk_mul_f32 v[2:3], v[24:25], v[2:3]
	v_pk_mul_f32 v[4:5], v[26:27], v[4:5]
	v_cvt_pk_bf16_f32 v2, v2, v3
	v_cvt_pk_bf16_f32 v3, v4, v5
	global_store_dwordx2 v[22:23], v[2:3], off sc1
	s_nop 1
	v_mov_b64_e32 v[2:3], v[196:197]
	v_mov_b64_e32 v[4:5], v[198:199]
	v_pk_mul_f32 v[24:25], v[38:39], v[0:1] op_sel_hi:[1,0]
	v_pk_mul_f32 v[26:27], v[30:31], v[0:1] op_sel_hi:[1,0]
	v_lshl_add_u64 v[22:23], v[20:21], 0, s[0:1]
	s_mov_b64 s[0:1], 0xb0
	v_pk_mul_f32 v[2:3], v[24:25], v[2:3]
	v_pk_mul_f32 v[4:5], v[26:27], v[4:5]
	v_cvt_pk_bf16_f32 v2, v2, v3
	v_cvt_pk_bf16_f32 v3, v4, v5
	global_store_dwordx2 v[22:23], v[2:3], off sc1
	s_nop 1
	s_waitcnt vmcnt(6)
	v_mov_b64_e32 v[2:3], v[152:153]
	v_mov_b64_e32 v[4:5], v[154:155]
	v_pk_mul_f32 v[24:25], v[36:37], v[0:1] op_sel_hi:[1,0]
	v_pk_mul_f32 v[26:27], v[28:29], v[0:1] op_sel_hi:[1,0]
	v_lshl_add_u64 v[22:23], v[20:21], 0, s[0:1]
	s_mov_b64 s[0:1], 0xc0
	v_pk_mul_f32 v[2:3], v[24:25], v[2:3]
	v_pk_mul_f32 v[4:5], v[26:27], v[4:5]
	v_cvt_pk_bf16_f32 v2, v2, v3
	v_cvt_pk_bf16_f32 v3, v4, v5
	global_store_dwordx2 v[22:23], v[2:3], off sc1
	s_nop 1
	v_mov_b64_e32 v[2:3], v[156:157]
	v_mov_b64_e32 v[4:5], v[158:159]
	v_pk_mul_f32 v[24:25], v[34:35], v[0:1] op_sel_hi:[1,0]
	v_lshl_add_u64 v[22:23], v[20:21], 0, s[0:1]
	s_mov_b64 s[0:1], 0xd0
	v_pk_mul_f32 v[2:3], v[24:25], v[2:3]
	v_pk_mul_f32 v[4:5], v[18:19], v[4:5]
	v_cvt_pk_bf16_f32 v2, v2, v3
	v_cvt_pk_bf16_f32 v3, v4, v5
	global_store_dwordx2 v[22:23], v[2:3], off sc1
	s_nop 1
	v_mov_b64_e32 v[2:3], v[168:169]
	v_mov_b64_e32 v[4:5], v[170:171]
	v_lshl_add_u64 v[18:19], v[20:21], 0, s[0:1]
	s_mov_b64 s[0:1], 0xe0
	v_pk_mul_f32 v[2:3], v[16:17], v[2:3]
	v_pk_mul_f32 v[4:5], v[14:15], v[4:5]
	v_cvt_pk_bf16_f32 v2, v2, v3
	v_cvt_pk_bf16_f32 v3, v4, v5
	global_store_dwordx2 v[18:19], v[2:3], off sc1
	s_nop 1
	v_mov_b64_e32 v[2:3], v[172:173]
	v_mov_b64_e32 v[4:5], v[174:175]
	v_lshl_add_u64 v[14:15], v[20:21], 0, s[0:1]
	s_mov_b64 s[0:1], 0xf0
	v_pk_mul_f32 v[2:3], v[12:13], v[2:3]
	v_pk_mul_f32 v[4:5], v[10:11], v[4:5]
	v_cvt_pk_bf16_f32 v2, v2, v3
	v_cvt_pk_bf16_f32 v3, v4, v5
	global_store_dwordx2 v[14:15], v[2:3], off sc1
	s_nop 1
	v_mov_b64_e32 v[2:3], v[176:177]
	v_mov_b64_e32 v[4:5], v[178:179]
	v_pk_mul_f32 v[2:3], v[6:7], v[2:3]
	v_pk_mul_f32 v[4:5], v[8:9], v[4:5]
	v_cvt_pk_bf16_f32 v2, v2, v3
	v_cvt_pk_bf16_f32 v3, v4, v5
	v_lshl_add_u64 v[4:5], v[20:21], 0, s[0:1]
	global_store_dwordx2 v[4:5], v[2:3], off sc1
	s_nop 1
	s_branch .LBB0_1595

.LBB0_2167:
	s_cmpk_gt_u32 s0, 0xff
	s_waitcnt lgkmcnt(0)
	s_barrier
	s_cbranch_scc1 .LBB0_2148
	s_lshl_b32 s0, s0, 8
	v_lshl_add_u32 v5, v207, 2, 0
	s_and_b32 s1, s0, 0xc000
	v_add_u32_e32 v6, s1, v5
	ds_read2st64_b32 v[10:11], v6 offset1:1
	ds_read2st64_b32 v[14:15], v6 offset0:2 offset1:3
	ds_read2st64_b32 v[86:87], v6 offset0:4 offset1:5
	ds_read2st64_b32 v[88:89], v6 offset0:6 offset1:7
	ds_read2st64_b32 v[90:91], v6 offset0:8 offset1:9
	ds_read2st64_b32 v[92:93], v6 offset0:10 offset1:11
	ds_read2st64_b32 v[94:95], v6 offset0:12 offset1:13
	ds_read2st64_b32 v[96:97], v6 offset0:14 offset1:15
	ds_read2st64_b32 v[98:99], v6 offset0:16 offset1:17
	ds_read2st64_b32 v[100:101], v6 offset0:18 offset1:19
	ds_read2st64_b32 v[102:103], v6 offset0:20 offset1:21
	ds_read2st64_b32 v[104:105], v6 offset0:22 offset1:23
	ds_read2st64_b32 v[106:107], v6 offset0:24 offset1:25
	ds_read2st64_b32 v[108:109], v6 offset0:26 offset1:27
	ds_read2st64_b32 v[110:111], v6 offset0:28 offset1:29
	ds_read2st64_b32 v[112:113], v6 offset0:30 offset1:31
	ds_read2st64_b32 v[114:115], v6 offset0:32 offset1:33
	ds_read2st64_b32 v[116:117], v6 offset0:34 offset1:35
	ds_read2st64_b32 v[118:119], v6 offset0:36 offset1:37
	ds_read2st64_b32 v[120:121], v6 offset0:38 offset1:39
	ds_read2st64_b32 v[122:123], v6 offset0:40 offset1:41
	ds_read2st64_b32 v[124:125], v6 offset0:42 offset1:43
	ds_read2st64_b32 v[126:127], v6 offset0:44 offset1:45
	ds_read2st64_b32 v[128:129], v6 offset0:46 offset1:47
	ds_read2st64_b32 v[12:13], v6 offset0:56 offset1:57
	ds_read2st64_b32 v[130:131], v6 offset0:58 offset1:59
	ds_read2st64_b32 v[2:3], v6 offset0:60 offset1:61
	ds_read_b32 v4, v6 offset:15872
	s_waitcnt lgkmcnt(14)
	v_pk_mul_f32 v[10:11], v[160:161], v[10:11]
	s_or_b32 s0, s0, 0x3f00
	v_pk_fma_f32 v[82:83], v[64:65], v[0:1], v[10:11] op_sel_hi:[1,0,1] neg_lo:[0,0,1] neg_hi:[0,0,1]
	v_pk_mul_f32 v[10:11], v[160:161], v[88:89]
	v_add_u32_e32 v5, s0, v5
	v_pk_fma_f32 v[70:71], v[70:71], v[0:1], v[10:11] op_sel_hi:[1,0,1] neg_lo:[0,0,1] neg_hi:[0,0,1]
	v_pk_mul_f32 v[10:11], v[160:161], v[86:87]
	ds_read_b32 v5, v5
	ds_read2st64_b32 v[132:133], v6 offset0:48 offset1:49
	ds_read2st64_b32 v[134:135], v6 offset0:50 offset1:51
	ds_read2st64_b32 v[136:137], v6 offset0:52 offset1:53
	ds_read2st64_b32 v[138:139], v6 offset0:54 offset1:55
	v_pk_fma_f32 v[86:87], v[68:69], v[0:1], v[10:11] op_sel_hi:[1,0,1] neg_lo:[0,0,1] neg_hi:[0,0,1]
	v_pk_mul_f32 v[10:11], v[160:161], v[92:93]
	s_waitcnt lgkmcnt(6)
	v_pk_mul_f32 v[2:3], v[160:161], v[2:3]
	v_pk_fma_f32 v[74:75], v[74:75], v[0:1], v[10:11] op_sel_hi:[1,0,1] neg_lo:[0,0,1] neg_hi:[0,0,1]
	v_pk_mul_f32 v[10:11], v[160:161], v[90:91]
	v_pk_fma_f32 v[6:7], v[28:29], v[0:1], v[2:3] op_sel_hi:[1,0,1] neg_lo:[0,0,1] neg_hi:[0,0,1]
	v_pk_fma_f32 v[90:91], v[72:73], v[0:1], v[10:11] op_sel_hi:[1,0,1] neg_lo:[0,0,1] neg_hi:[0,0,1]
	v_pk_mul_f32 v[10:11], v[160:161], v[96:97]
	s_waitcnt lgkmcnt(4)
	v_pk_mul_f32 v[2:3], v[160:161], v[4:5]
	v_pk_fma_f32 v[68:69], v[78:79], v[0:1], v[10:11] op_sel_hi:[1,0,1] neg_lo:[0,0,1] neg_hi:[0,0,1]
	v_pk_mul_f32 v[10:11], v[160:161], v[94:95]
	v_pk_fma_f32 v[8:9], v[30:31], v[0:1], v[2:3] op_sel_hi:[1,0,1] neg_lo:[0,0,1] neg_hi:[0,0,1]
	v_pk_fma_f32 v[88:89], v[76:77], v[0:1], v[10:11] op_sel_hi:[1,0,1] neg_lo:[0,0,1] neg_hi:[0,0,1]
	v_pk_mul_f32 v[10:11], v[160:161], v[100:101]
	v_pk_mul_f32 v[14:15], v[160:161], v[14:15]
	v_pk_fma_f32 v[64:65], v[50:51], v[0:1], v[10:11] op_sel_hi:[1,0,1] neg_lo:[0,0,1] neg_hi:[0,0,1]
	v_pk_mul_f32 v[10:11], v[160:161], v[98:99]
	v_pk_fma_f32 v[66:67], v[66:67], v[0:1], v[14:15] op_sel_hi:[1,0,1] neg_lo:[0,0,1] neg_hi:[0,0,1]
	v_pk_fma_f32 v[78:79], v[48:49], v[0:1], v[10:11] op_sel_hi:[1,0,1] neg_lo:[0,0,1] neg_hi:[0,0,1]
	v_pk_mul_f32 v[10:11], v[160:161], v[104:105]
	v_pk_mul_f32 v[142:143], v[82:83], v[82:83]
	v_pk_fma_f32 v[54:55], v[54:55], v[0:1], v[10:11] op_sel_hi:[1,0,1] neg_lo:[0,0,1] neg_hi:[0,0,1]
	v_pk_mul_f32 v[10:11], v[160:161], v[102:103]
	v_pk_mul_f32 v[12:13], v[160:161], v[12:13]
	v_pk_fma_f32 v[76:77], v[52:53], v[0:1], v[10:11] op_sel_hi:[1,0,1] neg_lo:[0,0,1] neg_hi:[0,0,1]
	v_pk_mul_f32 v[10:11], v[160:161], v[108:109]
	global_load_dwordx4 v[2:5], v164, s[38:39] offset:512
	global_load_dwordx4 v[152:155], v164, s[38:39] offset:544
	global_load_dwordx4 v[156:159], v164, s[38:39] offset:576
	global_load_dwordx4 v[168:171], v164, s[38:39] offset:608
	global_load_dwordx4 v[172:175], v164, s[38:39] offset:640
	global_load_dwordx4 v[176:179], v164, s[38:39] offset:672
	global_load_dwordx4 v[180:183], v164, s[38:39] offset:704
	global_load_dwordx4 v[184:187], v164, s[38:39] offset:736
	global_load_dwordx4 v[188:191], v164, s[38:39] offset:768
	global_load_dwordx4 v[192:195], v164, s[38:39] offset:800
	global_load_dwordx4 v[196:199], v164, s[38:39] offset:832
	v_pk_fma_f32 v[50:51], v[58:59], v[0:1], v[10:11] op_sel_hi:[1,0,1] neg_lo:[0,0,1] neg_hi:[0,0,1]
	v_pk_mul_f32 v[10:11], v[160:161], v[106:107]
	v_pk_mul_f32 v[140:141], v[66:67], v[66:67]
	v_pk_fma_f32 v[72:73], v[56:57], v[0:1], v[10:11] op_sel_hi:[1,0,1] neg_lo:[0,0,1] neg_hi:[0,0,1]
	v_pk_mul_f32 v[10:11], v[160:161], v[112:113]
	v_pk_fma_f32 v[12:13], v[24:25], v[0:1], v[12:13] op_sel_hi:[1,0,1] neg_lo:[0,0,1] neg_hi:[0,0,1]
	v_pk_fma_f32 v[48:49], v[62:63], v[0:1], v[10:11] op_sel_hi:[1,0,1] neg_lo:[0,0,1] neg_hi:[0,0,1]
	v_pk_mul_f32 v[10:11], v[160:161], v[110:111]
	v_pk_mul_f32 v[146:147], v[86:87], v[86:87]
	v_pk_fma_f32 v[58:59], v[60:61], v[0:1], v[10:11] op_sel_hi:[1,0,1] neg_lo:[0,0,1] neg_hi:[0,0,1]
	v_pk_mul_f32 v[10:11], v[160:161], v[116:117]
	v_pk_mul_f32 v[144:145], v[70:71], v[70:71]
	v_pk_fma_f32 v[34:35], v[34:35], v[0:1], v[10:11] op_sel_hi:[1,0,1] neg_lo:[0,0,1] neg_hi:[0,0,1]
	v_pk_mul_f32 v[10:11], v[160:161], v[114:115]
	v_pk_mul_f32 v[148:149], v[90:91], v[90:91]
	v_pk_fma_f32 v[56:57], v[32:33], v[0:1], v[10:11] op_sel_hi:[1,0,1] neg_lo:[0,0,1] neg_hi:[0,0,1]
	v_pk_mul_f32 v[10:11], v[160:161], v[120:121]
	v_pk_mul_f32 v[92:93], v[74:75], v[74:75]
	v_pk_fma_f32 v[32:33], v[38:39], v[0:1], v[10:11] op_sel_hi:[1,0,1] neg_lo:[0,0,1] neg_hi:[0,0,1]
	v_pk_mul_f32 v[10:11], v[160:161], v[118:119]
	v_pk_mul_f32 v[94:95], v[88:89], v[88:89]
	v_pk_fma_f32 v[52:53], v[36:37], v[0:1], v[10:11] op_sel_hi:[1,0,1] neg_lo:[0,0,1] neg_hi:[0,0,1]
	v_pk_mul_f32 v[10:11], v[160:161], v[124:125]
	v_pk_mul_f32 v[96:97], v[68:69], v[68:69]
	v_pk_fma_f32 v[30:31], v[42:43], v[0:1], v[10:11] op_sel_hi:[1,0,1] neg_lo:[0,0,1] neg_hi:[0,0,1]
	v_pk_mul_f32 v[10:11], v[160:161], v[122:123]
	v_pk_mul_f32 v[98:99], v[78:79], v[78:79]
	v_pk_fma_f32 v[40:41], v[40:41], v[0:1], v[10:11] op_sel_hi:[1,0,1] neg_lo:[0,0,1] neg_hi:[0,0,1]
	v_pk_mul_f32 v[10:11], v[160:161], v[128:129]
	v_pk_mul_f32 v[100:101], v[64:65], v[64:65]
	v_pk_fma_f32 v[28:29], v[46:47], v[0:1], v[10:11] op_sel_hi:[1,0,1] neg_lo:[0,0,1] neg_hi:[0,0,1]
	v_pk_mul_f32 v[10:11], v[160:161], v[126:127]
	v_pk_mul_f32 v[102:103], v[76:77], v[76:77]
	v_pk_fma_f32 v[38:39], v[44:45], v[0:1], v[10:11] op_sel_hi:[1,0,1] neg_lo:[0,0,1] neg_hi:[0,0,1]
	s_waitcnt lgkmcnt(2)
	v_pk_mul_f32 v[10:11], v[160:161], v[134:135]
	v_pk_mul_f32 v[104:105], v[54:55], v[54:55]
	v_pk_fma_f32 v[18:19], v[18:19], v[0:1], v[10:11] op_sel_hi:[1,0,1] neg_lo:[0,0,1] neg_hi:[0,0,1]
	v_pk_mul_f32 v[10:11], v[160:161], v[132:133]
	v_pk_mul_f32 v[106:107], v[72:73], v[72:73]
	v_pk_fma_f32 v[36:37], v[16:17], v[0:1], v[10:11] op_sel_hi:[1,0,1] neg_lo:[0,0,1] neg_hi:[0,0,1]
	s_waitcnt lgkmcnt(0)
	v_pk_mul_f32 v[10:11], v[160:161], v[138:139]
	v_pk_mul_f32 v[108:109], v[50:51], v[50:51]
	v_pk_fma_f32 v[14:15], v[22:23], v[0:1], v[10:11] op_sel_hi:[1,0,1] neg_lo:[0,0,1] neg_hi:[0,0,1]
	v_pk_mul_f32 v[10:11], v[160:161], v[136:137]
	v_pk_mul_f32 v[60:61], v[58:59], v[58:59]
	v_pk_fma_f32 v[16:17], v[20:21], v[0:1], v[10:11] op_sel_hi:[1,0,1] neg_lo:[0,0,1] neg_hi:[0,0,1]
	v_pk_mul_f32 v[10:11], v[160:161], v[130:131]
	v_pk_mul_f32 v[62:63], v[48:49], v[48:49]
	v_pk_fma_f32 v[10:11], v[26:27], v[0:1], v[10:11] op_sel_hi:[1,0,1] neg_lo:[0,0,1] neg_hi:[0,0,1]
	v_add_f32_e32 v0, v142, v143
	v_add_f32_e32 v0, v0, v140
	v_add_f32_e32 v0, v0, v141
	v_add_f32_e32 v0, v0, v146
	v_add_f32_e32 v0, v0, v147
	v_add_f32_e32 v0, v0, v144
	v_add_f32_e32 v0, v0, v145
	v_add_f32_e32 v0, v0, v148
	v_add_f32_e32 v0, v0, v149
	v_add_f32_e32 v0, v0, v92
	v_add_f32_e32 v0, v0, v93
	v_add_f32_e32 v0, v0, v94
	v_add_f32_e32 v0, v0, v95
	v_add_f32_e32 v0, v0, v96
	v_add_f32_e32 v0, v0, v97
	v_add_f32_e32 v0, v0, v98
	v_add_f32_e32 v0, v0, v99
	v_add_f32_e32 v0, v0, v100
	v_add_f32_e32 v0, v0, v101
	v_add_f32_e32 v0, v0, v102
	v_add_f32_e32 v0, v0, v103
	v_add_f32_e32 v0, v0, v104
	v_add_f32_e32 v0, v0, v105
	v_add_f32_e32 v0, v0, v106
	v_add_f32_e32 v0, v0, v107
	v_add_f32_e32 v0, v0, v108
	v_add_f32_e32 v0, v0, v109
	v_add_f32_e32 v0, v0, v60
	v_add_f32_e32 v0, v0, v61
	v_add_f32_e32 v0, v0, v62
	v_pk_mul_f32 v[112:113], v[56:57], v[56:57]
	v_add_f32_e32 v0, v0, v63
	v_add_f32_e32 v0, v0, v112
	v_pk_mul_f32 v[110:111], v[34:35], v[34:35]
	v_add_f32_e32 v0, v0, v113
	v_add_f32_e32 v0, v0, v110
	v_pk_mul_f32 v[116:117], v[52:53], v[52:53]
	v_add_f32_e32 v0, v0, v111
	v_add_f32_e32 v0, v0, v116
	v_pk_mul_f32 v[114:115], v[32:33], v[32:33]
	v_add_f32_e32 v0, v0, v117
	v_add_f32_e32 v0, v0, v114
	v_pk_mul_f32 v[118:119], v[40:41], v[40:41]
	v_add_f32_e32 v0, v0, v115
	v_add_f32_e32 v0, v0, v118
	v_pk_mul_f32 v[42:43], v[30:31], v[30:31]
	v_add_f32_e32 v0, v0, v119
	v_add_f32_e32 v0, v0, v42
	v_pk_mul_f32 v[44:45], v[38:39], v[38:39]
	v_add_f32_e32 v0, v0, v43
	v_add_f32_e32 v0, v0, v44
	v_pk_mul_f32 v[46:47], v[28:29], v[28:29]
	v_add_f32_e32 v0, v0, v45
	v_add_f32_e32 v0, v0, v46
	v_pk_mul_f32 v[122:123], v[36:37], v[36:37]
	v_add_f32_e32 v0, v0, v47
	v_add_f32_e32 v0, v0, v122
	v_pk_mul_f32 v[120:121], v[18:19], v[18:19]
	v_add_f32_e32 v0, v0, v123
	v_add_f32_e32 v0, v0, v120
	v_pk_mul_f32 v[20:21], v[16:17], v[16:17]
	v_add_f32_e32 v0, v0, v121
	v_add_f32_e32 v0, v0, v20
	v_pk_mul_f32 v[22:23], v[14:15], v[14:15]
	v_add_f32_e32 v0, v0, v21
	v_add_f32_e32 v0, v0, v22
	v_pk_mul_f32 v[24:25], v[12:13], v[12:13]
	v_add_f32_e32 v0, v0, v23
	v_add_f32_e32 v0, v0, v24
	v_pk_mul_f32 v[26:27], v[10:11], v[10:11]
	v_add_f32_e32 v0, v0, v25
	v_add_f32_e32 v0, v0, v26
	v_pk_mul_f32 v[80:81], v[6:7], v[6:7]
	v_add_f32_e32 v0, v0, v27
	v_add_f32_e32 v0, v0, v80
	v_pk_mul_f32 v[84:85], v[8:9], v[8:9]
	v_add_f32_e32 v0, v0, v81
	v_add_f32_e32 v0, v0, v84
	v_add_f32_e32 v22, v0, v85
	ds_bpermute_b32 v23, v165, v22
	v_lshlrev_b32_e32 v0, 1, v162
	v_lshl_add_u64 v[20:21], s[46:47], 0, v[0:1]
	v_lshl_add_u64 v[20:21], v[20:21], 0, v[166:167]
	s_waitcnt lgkmcnt(0)
	v_add_f32_e32 v0, v22, v23
	v_fmamk_f32 v0, v0, 0x3c000000, v205
	v_mul_f32_e32 v22, 0x4b800000, v0
	v_cmp_gt_f32_e32 vcc, s65, v0
	s_nop 1
	v_cndmask_b32_e32 v0, v0, v22, vcc
	v_rsq_f32_e32 v22, v0
	v_lshlrev_b32_e32 v0, 3, v163
	v_lshl_add_u64 v[20:21], v[20:21], 0, v[0:1]
	v_mul_f32_e32 v0, 0x45800000, v22
	v_cndmask_b32_e32 v0, v22, v0, vcc
	v_mul_f32_e32 v0, 0x3ee34c56, v0
	v_pk_mul_f32 v[22:23], v[82:83], v[0:1] op_sel_hi:[1,0]
	v_pk_mul_f32 v[24:25], v[86:87], v[0:1] op_sel_hi:[1,0]
	s_waitcnt vmcnt(0)
	v_pk_mul_f32 v[2:3], v[2:3], v[22:23]
	v_pk_mul_f32 v[22:23], v[66:67], v[0:1] op_sel_hi:[1,0]
	v_cvt_pk_bf16_f32 v2, v2, v3
	v_pk_mul_f32 v[4:5], v[4:5], v[22:23]
	v_lshl_add_u64 v[22:23], v[20:21], 0, 16
	v_cvt_pk_bf16_f32 v3, v4, v5
	global_store_dwordx2 v[20:21], v[2:3], off sc1
	s_nop 1
	v_mov_b64_e32 v[2:3], v[152:153]
	v_mov_b64_e32 v[4:5], v[154:155]
	v_pk_mul_f32 v[26:27], v[74:75], v[0:1] op_sel_hi:[1,0]
	v_pk_mul_f32 v[18:19], v[18:19], v[0:1] op_sel_hi:[1,0]
	v_pk_mul_f32 v[16:17], v[16:17], v[0:1] op_sel_hi:[1,0]
	v_pk_mul_f32 v[14:15], v[14:15], v[0:1] op_sel_hi:[1,0]
	v_pk_mul_f32 v[12:13], v[12:13], v[0:1] op_sel_hi:[1,0]
	v_pk_mul_f32 v[10:11], v[10:11], v[0:1] op_sel_hi:[1,0]
	v_pk_mul_f32 v[6:7], v[6:7], v[0:1] op_sel_hi:[1,0]
	v_pk_mul_f32 v[8:9], v[8:9], v[0:1] op_sel_hi:[1,0]
	v_pk_mul_f32 v[2:3], v[2:3], v[24:25]
	v_pk_mul_f32 v[24:25], v[70:71], v[0:1] op_sel_hi:[1,0]
	v_cvt_pk_bf16_f32 v2, v2, v3
	v_pk_mul_f32 v[4:5], v[4:5], v[24:25]
	v_pk_mul_f32 v[24:25], v[90:91], v[0:1] op_sel_hi:[1,0]
	v_cvt_pk_bf16_f32 v3, v4, v5
	global_store_dwordx2 v[22:23], v[2:3], off sc1
	s_nop 1
	v_mov_b64_e32 v[2:3], v[156:157]
	v_mov_b64_e32 v[4:5], v[158:159]
	v_lshl_add_u64 v[22:23], v[20:21], 0, 32
	v_pk_mul_f32 v[2:3], v[2:3], v[24:25]
	v_pk_mul_f32 v[4:5], v[4:5], v[26:27]
	v_cvt_pk_bf16_f32 v2, v2, v3
	v_cvt_pk_bf16_f32 v3, v4, v5
	global_store_dwordx2 v[22:23], v[2:3], off sc1
	s_nop 1
	v_mov_b64_e32 v[2:3], v[168:169]
	v_mov_b64_e32 v[4:5], v[170:171]
	v_pk_mul_f32 v[24:25], v[88:89], v[0:1] op_sel_hi:[1,0]
	v_pk_mul_f32 v[26:27], v[68:69], v[0:1] op_sel_hi:[1,0]
	v_lshl_add_u64 v[22:23], v[20:21], 0, 48
	v_pk_mul_f32 v[2:3], v[2:3], v[24:25]
	v_pk_mul_f32 v[4:5], v[4:5], v[26:27]
	v_cvt_pk_bf16_f32 v2, v2, v3
	v_cvt_pk_bf16_f32 v3, v4, v5
	global_store_dwordx2 v[22:23], v[2:3], off sc1
	s_nop 1
	v_mov_b64_e32 v[2:3], v[172:173]
	v_mov_b64_e32 v[4:5], v[174:175]
	v_pk_mul_f32 v[24:25], v[78:79], v[0:1] op_sel_hi:[1,0]
	v_pk_mul_f32 v[26:27], v[64:65], v[0:1] op_sel_hi:[1,0]
	v_lshl_add_u64 v[22:23], v[20:21], 0, 64
	v_pk_mul_f32 v[2:3], v[2:3], v[24:25]
	v_pk_mul_f32 v[4:5], v[4:5], v[26:27]
	v_cvt_pk_bf16_f32 v2, v2, v3
	v_cvt_pk_bf16_f32 v3, v4, v5
	global_store_dwordx2 v[22:23], v[2:3], off sc1
	s_nop 1
	v_mov_b64_e32 v[2:3], v[176:177]
	v_mov_b64_e32 v[4:5], v[178:179]
	global_load_dwordx4 v[152:155], v164, s[38:39] offset:864
	global_load_dwordx4 v[156:159], v164, s[38:39] offset:896
	global_load_dwordx4 v[168:171], v164, s[38:39] offset:928
	global_load_dwordx4 v[172:175], v164, s[38:39] offset:960
	global_load_dwordx4 v[176:179], v164, s[38:39] offset:992
	v_pk_mul_f32 v[24:25], v[76:77], v[0:1] op_sel_hi:[1,0]
	v_pk_mul_f32 v[26:27], v[54:55], v[0:1] op_sel_hi:[1,0]
	v_lshl_add_u64 v[22:23], v[20:21], 0, s[28:29]
	v_pk_mul_f32 v[2:3], v[2:3], v[24:25]
	v_pk_mul_f32 v[4:5], v[4:5], v[26:27]
	v_cvt_pk_bf16_f32 v2, v2, v3
	v_cvt_pk_bf16_f32 v3, v4, v5
	global_store_dwordx2 v[22:23], v[2:3], off sc1
	s_nop 1
	v_mov_b64_e32 v[2:3], v[180:181]
	v_mov_b64_e32 v[4:5], v[182:183]
	v_pk_mul_f32 v[24:25], v[72:73], v[0:1] op_sel_hi:[1,0]
	v_pk_mul_f32 v[26:27], v[50:51], v[0:1] op_sel_hi:[1,0]
	v_lshl_add_u64 v[22:23], v[20:21], 0, s[36:37]
	v_pk_mul_f32 v[2:3], v[2:3], v[24:25]
	v_pk_mul_f32 v[4:5], v[4:5], v[26:27]
	v_cvt_pk_bf16_f32 v2, v2, v3
	v_cvt_pk_bf16_f32 v3, v4, v5
	global_store_dwordx2 v[22:23], v[2:3], off sc1
	s_nop 1
	v_mov_b64_e32 v[2:3], v[184:185]
	v_mov_b64_e32 v[4:5], v[186:187]
	v_pk_mul_f32 v[24:25], v[58:59], v[0:1] op_sel_hi:[1,0]
	v_pk_mul_f32 v[26:27], v[48:49], v[0:1] op_sel_hi:[1,0]
	v_lshl_add_u64 v[22:23], v[20:21], 0, s[40:41]
	v_pk_mul_f32 v[2:3], v[24:25], v[2:3]
	v_pk_mul_f32 v[4:5], v[26:27], v[4:5]
	v_cvt_pk_bf16_f32 v2, v2, v3
	v_cvt_pk_bf16_f32 v3, v4, v5
	global_store_dwordx2 v[22:23], v[2:3], off sc1
	s_nop 1
	v_mov_b64_e32 v[2:3], v[188:189]
	v_mov_b64_e32 v[4:5], v[190:191]
	v_pk_mul_f32 v[24:25], v[56:57], v[0:1] op_sel_hi:[1,0]
	v_pk_mul_f32 v[26:27], v[34:35], v[0:1] op_sel_hi:[1,0]
	v_lshl_add_u64 v[22:23], v[20:21], 0, s[52:53]
	v_pk_mul_f32 v[2:3], v[24:25], v[2:3]
	v_pk_mul_f32 v[4:5], v[26:27], v[4:5]
	v_cvt_pk_bf16_f32 v2, v2, v3
	v_cvt_pk_bf16_f32 v3, v4, v5
	global_store_dwordx2 v[22:23], v[2:3], off sc1
	s_nop 1
	v_mov_b64_e32 v[2:3], v[192:193]
	v_mov_b64_e32 v[4:5], v[194:195]
	v_pk_mul_f32 v[24:25], v[52:53], v[0:1] op_sel_hi:[1,0]
	v_pk_mul_f32 v[26:27], v[32:33], v[0:1] op_sel_hi:[1,0]
	v_lshl_add_u64 v[22:23], v[20:21], 0, s[54:55]
	v_pk_mul_f32 v[2:3], v[24:25], v[2:3]
	v_pk_mul_f32 v[4:5], v[26:27], v[4:5]
	v_cvt_pk_bf16_f32 v2, v2, v3
	v_cvt_pk_bf16_f32 v3, v4, v5
	global_store_dwordx2 v[22:23], v[2:3], off sc1
	s_nop 1
	v_mov_b64_e32 v[2:3], v[196:197]
	v_mov_b64_e32 v[4:5], v[198:199]
	v_pk_mul_f32 v[24:25], v[40:41], v[0:1] op_sel_hi:[1,0]
	v_pk_mul_f32 v[26:27], v[30:31], v[0:1] op_sel_hi:[1,0]
	v_lshl_add_u64 v[22:23], v[20:21], 0, s[56:57]
	v_pk_mul_f32 v[2:3], v[24:25], v[2:3]
	v_pk_mul_f32 v[4:5], v[26:27], v[4:5]
	v_cvt_pk_bf16_f32 v2, v2, v3
	v_cvt_pk_bf16_f32 v3, v4, v5
	global_store_dwordx2 v[22:23], v[2:3], off sc1
	s_nop 1
	s_waitcnt vmcnt(6)
	v_mov_b64_e32 v[2:3], v[152:153]
	v_mov_b64_e32 v[4:5], v[154:155]
	v_pk_mul_f32 v[24:25], v[38:39], v[0:1] op_sel_hi:[1,0]
	v_pk_mul_f32 v[26:27], v[28:29], v[0:1] op_sel_hi:[1,0]
	v_lshl_add_u64 v[22:23], v[20:21], 0, s[58:59]
	v_pk_mul_f32 v[2:3], v[24:25], v[2:3]
	v_pk_mul_f32 v[4:5], v[26:27], v[4:5]
	v_cvt_pk_bf16_f32 v2, v2, v3
	v_cvt_pk_bf16_f32 v3, v4, v5
	global_store_dwordx2 v[22:23], v[2:3], off sc1
	s_nop 1
	v_mov_b64_e32 v[2:3], v[156:157]
	v_mov_b64_e32 v[4:5], v[158:159]
	v_pk_mul_f32 v[24:25], v[36:37], v[0:1] op_sel_hi:[1,0]
	v_lshl_add_u64 v[22:23], v[20:21], 0, s[70:71]
	v_pk_mul_f32 v[2:3], v[24:25], v[2:3]
	v_pk_mul_f32 v[4:5], v[18:19], v[4:5]
	v_cvt_pk_bf16_f32 v2, v2, v3
	v_cvt_pk_bf16_f32 v3, v4, v5
	global_store_dwordx2 v[22:23], v[2:3], off sc1
	s_nop 1
	v_mov_b64_e32 v[2:3], v[168:169]
	v_mov_b64_e32 v[4:5], v[170:171]
	v_lshl_add_u64 v[18:19], v[20:21], 0, s[72:73]
	v_pk_mul_f32 v[2:3], v[16:17], v[2:3]
	v_pk_mul_f32 v[4:5], v[14:15], v[4:5]
	v_cvt_pk_bf16_f32 v2, v2, v3
	v_cvt_pk_bf16_f32 v3, v4, v5
	global_store_dwordx2 v[18:19], v[2:3], off sc1
	s_nop 1
	v_mov_b64_e32 v[2:3], v[172:173]
	v_mov_b64_e32 v[4:5], v[174:175]
	v_lshl_add_u64 v[14:15], v[20:21], 0, s[74:75]
	v_pk_mul_f32 v[2:3], v[12:13], v[2:3]
	v_pk_mul_f32 v[4:5], v[10:11], v[4:5]
	v_cvt_pk_bf16_f32 v2, v2, v3
	v_cvt_pk_bf16_f32 v3, v4, v5
	global_store_dwordx2 v[14:15], v[2:3], off sc1
	s_nop 1
	v_mov_b64_e32 v[2:3], v[176:177]
	v_mov_b64_e32 v[4:5], v[178:179]
	v_pk_mul_f32 v[2:3], v[6:7], v[2:3]
	v_pk_mul_f32 v[4:5], v[8:9], v[4:5]
	v_cvt_pk_bf16_f32 v2, v2, v3
	v_cvt_pk_bf16_f32 v3, v4, v5
	v_lshl_add_u64 v[4:5], v[20:21], 0, s[76:77]
	global_store_dwordx2 v[4:5], v[2:3], off sc1
	s_nop 1
	s_branch .LBB0_2148
